# two-level barrier: global-counter poll interval s_sleep 16 -> 3 (only 8 arrivals share that line now)
# speedup vs baseline: 1.1064x; 1.0068x over previous
.Lhb1_poll:
	global_load_dword v1, v211, s[44:45] offset:256 sc1
	s_waitcnt vmcnt(0)
	v_cmp_gt_u32_e32 vcc, s4, v1
	s_cbranch_vccz .Lhb1_done
	s_sleep 3
	s_add_i32 s5, s5, 1
	s_cmp_lt_u32 s5, 0x20000
	s_cbranch_scc1 .Lhb1_poll
